# group-norm rescale passes use 16-byte (dwordx4) loads/stores with a per-lane column remap instead of 8-byte row-strided ones
# speedup vs baseline: 1.0117x; 1.0117x over previous
; DI float bf_lo(unsigned u) { return __uint_as_float(u << 16); }
; DI float bf_hi(unsigned u) { return __uint_as_float(u & 0xffff0000u); }
; DI float frsq(float x) { return __builtin_amdgcn_rsqf(x); }
; DI float xhalf(float v) { return __shfl_xor(v, 32); }
; DI void phase_attn(const Params& p, int layer, char* smem) {
;     ...
;       ssq += xhalf(ssq);
;       const float rstd = frsq(ssq * (1.f / 256.f) + EPS);
; #pragma unroll
;       for (int j = 0; j < 32; ++j) {
;         uint2* a = (uint2*)(ocat + (size_t)qtok * 1024 + 768 + 8 * j + 4 * h);
;         uint2 u = *a;
;         u.x = pk_bf16(bf_lo(u.x) * rstd, bf_hi(u.x) * rstd);
;         u.y = pk_bf16(bf_lo(u.y) * rstd, bf_hi(u.y) * rstd);
;         *a = u;
;       }
.LBB0_288:
	v_and_b32_e32 v4, 32, v228
	v_lshrrev_b32_e32 v4, 2, v4
	v_mov_b32_e32 v5, 0
	v_lshl_add_u64 v[6:7], v[112:113], 0, v[4:5]
	global_load_dwordx4 v[10:13], v[6:7], off offset:1536
	global_load_dwordx4 v[14:17], v[6:7], off offset:1568
	global_load_dwordx4 v[18:21], v[6:7], off offset:1600
	global_load_dwordx4 v[22:25], v[6:7], off offset:1632
	global_load_dwordx4 v[26:29], v[6:7], off offset:1664
	global_load_dwordx4 v[30:33], v[6:7], off offset:1696
	global_load_dwordx4 v[34:37], v[6:7], off offset:1728
	global_load_dwordx4 v[38:41], v[6:7], off offset:1760
	global_load_dwordx4 v[42:45], v[6:7], off offset:1792
	global_load_dwordx4 v[46:49], v[6:7], off offset:1824
	global_load_dwordx4 v[50:53], v[6:7], off offset:1856
	global_load_dwordx4 v[54:57], v[6:7], off offset:1888
	global_load_dwordx4 v[58:61], v[6:7], off offset:1920
	global_load_dwordx4 v[62:65], v[6:7], off offset:1952
	global_load_dwordx4 v[66:69], v[6:7], off offset:1984
	global_load_dwordx4 v[70:73], v[6:7], off offset:2016
	ds_bpermute_b32 v0, v180, v179
	s_mov_b64 s[0:1], 0
	v_readlane_b32 s44, v255, 20
	v_readlane_b32 s8, v255, 21
	s_waitcnt lgkmcnt(0)
	v_add_f32_e32 v0, v179, v0
	v_fmamk_f32 v0, v0, 0x3b800000, v229
	v_rsq_f32_e32 v0, v0
	s_waitcnt vmcnt(15)
	v_lshlrev_b32_e32 v4, 16, v10
	v_and_b32_e32 v5, 0xffff0000, v10
	v_pk_mul_f32 v[4:5], v[0:1], v[4:5] op_sel_hi:[0,1]
	v_cvt_pk_bf16_f32 v10, v4, v5
	v_lshlrev_b32_e32 v4, 16, v11
	v_and_b32_e32 v5, 0xffff0000, v11
	v_pk_mul_f32 v[4:5], v[0:1], v[4:5] op_sel_hi:[0,1]
	v_cvt_pk_bf16_f32 v11, v4, v5
	v_lshlrev_b32_e32 v4, 16, v12
	v_and_b32_e32 v5, 0xffff0000, v12
	v_pk_mul_f32 v[4:5], v[0:1], v[4:5] op_sel_hi:[0,1]
	v_cvt_pk_bf16_f32 v12, v4, v5
	v_lshlrev_b32_e32 v4, 16, v13
	v_and_b32_e32 v5, 0xffff0000, v13
	v_pk_mul_f32 v[4:5], v[0:1], v[4:5] op_sel_hi:[0,1]
	v_cvt_pk_bf16_f32 v13, v4, v5
	global_store_dwordx4 v[6:7], v[10:13], off offset:1536
	s_waitcnt vmcnt(15)
	v_lshlrev_b32_e32 v4, 16, v14
	v_and_b32_e32 v5, 0xffff0000, v14
	v_pk_mul_f32 v[4:5], v[0:1], v[4:5] op_sel_hi:[0,1]
	v_cvt_pk_bf16_f32 v14, v4, v5
	v_lshlrev_b32_e32 v4, 16, v15
	v_and_b32_e32 v5, 0xffff0000, v15
	v_pk_mul_f32 v[4:5], v[0:1], v[4:5] op_sel_hi:[0,1]
	v_cvt_pk_bf16_f32 v15, v4, v5
	v_lshlrev_b32_e32 v4, 16, v16
	v_and_b32_e32 v5, 0xffff0000, v16
	v_pk_mul_f32 v[4:5], v[0:1], v[4:5] op_sel_hi:[0,1]
	v_cvt_pk_bf16_f32 v16, v4, v5
	v_lshlrev_b32_e32 v4, 16, v17
	v_and_b32_e32 v5, 0xffff0000, v17
	v_pk_mul_f32 v[4:5], v[0:1], v[4:5] op_sel_hi:[0,1]
	v_cvt_pk_bf16_f32 v17, v4, v5
	global_store_dwordx4 v[6:7], v[14:17], off offset:1568
	s_waitcnt vmcnt(15)
	v_lshlrev_b32_e32 v4, 16, v18
	v_and_b32_e32 v5, 0xffff0000, v18
	v_pk_mul_f32 v[4:5], v[0:1], v[4:5] op_sel_hi:[0,1]
	v_cvt_pk_bf16_f32 v18, v4, v5
	v_lshlrev_b32_e32 v4, 16, v19
	v_and_b32_e32 v5, 0xffff0000, v19
	v_pk_mul_f32 v[4:5], v[0:1], v[4:5] op_sel_hi:[0,1]
	v_cvt_pk_bf16_f32 v19, v4, v5
	v_lshlrev_b32_e32 v4, 16, v20
	v_and_b32_e32 v5, 0xffff0000, v20
	v_pk_mul_f32 v[4:5], v[0:1], v[4:5] op_sel_hi:[0,1]
	v_cvt_pk_bf16_f32 v20, v4, v5
	v_lshlrev_b32_e32 v4, 16, v21
	v_and_b32_e32 v5, 0xffff0000, v21
	v_pk_mul_f32 v[4:5], v[0:1], v[4:5] op_sel_hi:[0,1]
	v_cvt_pk_bf16_f32 v21, v4, v5
	global_store_dwordx4 v[6:7], v[18:21], off offset:1600
	s_waitcnt vmcnt(15)
	v_lshlrev_b32_e32 v4, 16, v22
	v_and_b32_e32 v5, 0xffff0000, v22
	v_pk_mul_f32 v[4:5], v[0:1], v[4:5] op_sel_hi:[0,1]
	v_cvt_pk_bf16_f32 v22, v4, v5
	v_lshlrev_b32_e32 v4, 16, v23
	v_and_b32_e32 v5, 0xffff0000, v23
	v_pk_mul_f32 v[4:5], v[0:1], v[4:5] op_sel_hi:[0,1]
	v_cvt_pk_bf16_f32 v23, v4, v5
	v_lshlrev_b32_e32 v4, 16, v24
	v_and_b32_e32 v5, 0xffff0000, v24
	v_pk_mul_f32 v[4:5], v[0:1], v[4:5] op_sel_hi:[0,1]
	v_cvt_pk_bf16_f32 v24, v4, v5
	v_lshlrev_b32_e32 v4, 16, v25
	v_and_b32_e32 v5, 0xffff0000, v25
	v_pk_mul_f32 v[4:5], v[0:1], v[4:5] op_sel_hi:[0,1]
	v_cvt_pk_bf16_f32 v25, v4, v5
	global_store_dwordx4 v[6:7], v[22:25], off offset:1632
	s_waitcnt vmcnt(15)
	v_lshlrev_b32_e32 v4, 16, v26
	v_and_b32_e32 v5, 0xffff0000, v26
	v_pk_mul_f32 v[4:5], v[0:1], v[4:5] op_sel_hi:[0,1]
	v_cvt_pk_bf16_f32 v26, v4, v5
	v_lshlrev_b32_e32 v4, 16, v27
	v_and_b32_e32 v5, 0xffff0000, v27
	v_pk_mul_f32 v[4:5], v[0:1], v[4:5] op_sel_hi:[0,1]
	v_cvt_pk_bf16_f32 v27, v4, v5
	v_lshlrev_b32_e32 v4, 16, v28
	v_and_b32_e32 v5, 0xffff0000, v28
	v_pk_mul_f32 v[4:5], v[0:1], v[4:5] op_sel_hi:[0,1]
	v_cvt_pk_bf16_f32 v28, v4, v5
	v_lshlrev_b32_e32 v4, 16, v29
	v_and_b32_e32 v5, 0xffff0000, v29
	v_pk_mul_f32 v[4:5], v[0:1], v[4:5] op_sel_hi:[0,1]
	v_cvt_pk_bf16_f32 v29, v4, v5
	global_store_dwordx4 v[6:7], v[26:29], off offset:1664
	s_waitcnt vmcnt(15)
	v_lshlrev_b32_e32 v4, 16, v30
	v_and_b32_e32 v5, 0xffff0000, v30
	v_pk_mul_f32 v[4:5], v[0:1], v[4:5] op_sel_hi:[0,1]
	v_cvt_pk_bf16_f32 v30, v4, v5
	v_lshlrev_b32_e32 v4, 16, v31
	v_and_b32_e32 v5, 0xffff0000, v31
	v_pk_mul_f32 v[4:5], v[0:1], v[4:5] op_sel_hi:[0,1]
	v_cvt_pk_bf16_f32 v31, v4, v5
	v_lshlrev_b32_e32 v4, 16, v32
	v_and_b32_e32 v5, 0xffff0000, v32
	v_pk_mul_f32 v[4:5], v[0:1], v[4:5] op_sel_hi:[0,1]
	v_cvt_pk_bf16_f32 v32, v4, v5
	v_lshlrev_b32_e32 v4, 16, v33
	v_and_b32_e32 v5, 0xffff0000, v33
	v_pk_mul_f32 v[4:5], v[0:1], v[4:5] op_sel_hi:[0,1]
	v_cvt_pk_bf16_f32 v33, v4, v5
	global_store_dwordx4 v[6:7], v[30:33], off offset:1696
	s_waitcnt vmcnt(15)
; DI float bf_lo(unsigned u) { return __uint_as_float(u << 16); }
; DI float bf_hi(unsigned u) { return __uint_as_float(u & 0xffff0000u); }
; DI void phase_attn(const Params& p, int layer, char* smem) {
;     ...
;       for (int j = 0; j < 32; ++j) {
;         uint2* a = (uint2*)(ocat + (size_t)qtok * 1024 + 768 + 8 * j + 4 * h);
;         uint2 u = *a;
;         u.x = pk_bf16(bf_lo(u.x) * rstd, bf_hi(u.x) * rstd);
;         u.y = pk_bf16(bf_lo(u.y) * rstd, bf_hi(u.y) * rstd);
;         *a = u;
;       }
	v_lshlrev_b32_e32 v4, 16, v34
	v_and_b32_e32 v5, 0xffff0000, v34
	v_pk_mul_f32 v[4:5], v[0:1], v[4:5] op_sel_hi:[0,1]
	v_cvt_pk_bf16_f32 v34, v4, v5
	v_lshlrev_b32_e32 v4, 16, v35
	v_and_b32_e32 v5, 0xffff0000, v35
	v_pk_mul_f32 v[4:5], v[0:1], v[4:5] op_sel_hi:[0,1]
	v_cvt_pk_bf16_f32 v35, v4, v5
	v_lshlrev_b32_e32 v4, 16, v36
	v_and_b32_e32 v5, 0xffff0000, v36
	v_pk_mul_f32 v[4:5], v[0:1], v[4:5] op_sel_hi:[0,1]
	v_cvt_pk_bf16_f32 v36, v4, v5
	v_lshlrev_b32_e32 v4, 16, v37
	v_and_b32_e32 v5, 0xffff0000, v37
	v_pk_mul_f32 v[4:5], v[0:1], v[4:5] op_sel_hi:[0,1]
	v_cvt_pk_bf16_f32 v37, v4, v5
	global_store_dwordx4 v[6:7], v[34:37], off offset:1728
	s_waitcnt vmcnt(15)
	v_lshlrev_b32_e32 v4, 16, v38
	v_and_b32_e32 v5, 0xffff0000, v38
	v_pk_mul_f32 v[4:5], v[0:1], v[4:5] op_sel_hi:[0,1]
	v_cvt_pk_bf16_f32 v38, v4, v5
	v_lshlrev_b32_e32 v4, 16, v39
	v_and_b32_e32 v5, 0xffff0000, v39
	v_pk_mul_f32 v[4:5], v[0:1], v[4:5] op_sel_hi:[0,1]
	v_cvt_pk_bf16_f32 v39, v4, v5
	v_lshlrev_b32_e32 v4, 16, v40
	v_and_b32_e32 v5, 0xffff0000, v40
	v_pk_mul_f32 v[4:5], v[0:1], v[4:5] op_sel_hi:[0,1]
	v_cvt_pk_bf16_f32 v40, v4, v5
	v_lshlrev_b32_e32 v4, 16, v41
	v_and_b32_e32 v5, 0xffff0000, v41
	v_pk_mul_f32 v[4:5], v[0:1], v[4:5] op_sel_hi:[0,1]
	v_cvt_pk_bf16_f32 v41, v4, v5
	global_store_dwordx4 v[6:7], v[38:41], off offset:1760
	s_waitcnt vmcnt(15)
	v_lshlrev_b32_e32 v4, 16, v42
	v_and_b32_e32 v5, 0xffff0000, v42
	v_pk_mul_f32 v[4:5], v[0:1], v[4:5] op_sel_hi:[0,1]
	v_cvt_pk_bf16_f32 v42, v4, v5
	v_lshlrev_b32_e32 v4, 16, v43
	v_and_b32_e32 v5, 0xffff0000, v43
	v_pk_mul_f32 v[4:5], v[0:1], v[4:5] op_sel_hi:[0,1]
	v_cvt_pk_bf16_f32 v43, v4, v5
	v_lshlrev_b32_e32 v4, 16, v44
	v_and_b32_e32 v5, 0xffff0000, v44
	v_pk_mul_f32 v[4:5], v[0:1], v[4:5] op_sel_hi:[0,1]
	v_cvt_pk_bf16_f32 v44, v4, v5
	v_lshlrev_b32_e32 v4, 16, v45
	v_and_b32_e32 v5, 0xffff0000, v45
	v_pk_mul_f32 v[4:5], v[0:1], v[4:5] op_sel_hi:[0,1]
	v_cvt_pk_bf16_f32 v45, v4, v5
	global_store_dwordx4 v[6:7], v[42:45], off offset:1792
	s_waitcnt vmcnt(15)
	v_lshlrev_b32_e32 v4, 16, v46
	v_and_b32_e32 v5, 0xffff0000, v46
	v_pk_mul_f32 v[4:5], v[0:1], v[4:5] op_sel_hi:[0,1]
	v_cvt_pk_bf16_f32 v46, v4, v5
	v_lshlrev_b32_e32 v4, 16, v47
	v_and_b32_e32 v5, 0xffff0000, v47
	v_pk_mul_f32 v[4:5], v[0:1], v[4:5] op_sel_hi:[0,1]
	v_cvt_pk_bf16_f32 v47, v4, v5
	v_lshlrev_b32_e32 v4, 16, v48
	v_and_b32_e32 v5, 0xffff0000, v48
	v_pk_mul_f32 v[4:5], v[0:1], v[4:5] op_sel_hi:[0,1]
	v_cvt_pk_bf16_f32 v48, v4, v5
	v_lshlrev_b32_e32 v4, 16, v49
	v_and_b32_e32 v5, 0xffff0000, v49
	v_pk_mul_f32 v[4:5], v[0:1], v[4:5] op_sel_hi:[0,1]
	v_cvt_pk_bf16_f32 v49, v4, v5
	global_store_dwordx4 v[6:7], v[46:49], off offset:1824
	s_waitcnt vmcnt(15)
	v_lshlrev_b32_e32 v4, 16, v50
	v_and_b32_e32 v5, 0xffff0000, v50
	v_pk_mul_f32 v[4:5], v[0:1], v[4:5] op_sel_hi:[0,1]
	v_cvt_pk_bf16_f32 v50, v4, v5
	v_lshlrev_b32_e32 v4, 16, v51
	v_and_b32_e32 v5, 0xffff0000, v51
	v_pk_mul_f32 v[4:5], v[0:1], v[4:5] op_sel_hi:[0,1]
	v_cvt_pk_bf16_f32 v51, v4, v5
	v_lshlrev_b32_e32 v4, 16, v52
	v_and_b32_e32 v5, 0xffff0000, v52
	v_pk_mul_f32 v[4:5], v[0:1], v[4:5] op_sel_hi:[0,1]
	v_cvt_pk_bf16_f32 v52, v4, v5
	v_lshlrev_b32_e32 v4, 16, v53
	v_and_b32_e32 v5, 0xffff0000, v53
	v_pk_mul_f32 v[4:5], v[0:1], v[4:5] op_sel_hi:[0,1]
	v_cvt_pk_bf16_f32 v53, v4, v5
	global_store_dwordx4 v[6:7], v[50:53], off offset:1856
	s_waitcnt vmcnt(15)
	v_lshlrev_b32_e32 v4, 16, v54
	v_and_b32_e32 v5, 0xffff0000, v54
	v_pk_mul_f32 v[4:5], v[0:1], v[4:5] op_sel_hi:[0,1]
	v_cvt_pk_bf16_f32 v54, v4, v5
	v_lshlrev_b32_e32 v4, 16, v55
	v_and_b32_e32 v5, 0xffff0000, v55
	v_pk_mul_f32 v[4:5], v[0:1], v[4:5] op_sel_hi:[0,1]
	v_cvt_pk_bf16_f32 v55, v4, v5
	v_lshlrev_b32_e32 v4, 16, v56
	v_and_b32_e32 v5, 0xffff0000, v56
	v_pk_mul_f32 v[4:5], v[0:1], v[4:5] op_sel_hi:[0,1]
	v_cvt_pk_bf16_f32 v56, v4, v5
	v_lshlrev_b32_e32 v4, 16, v57
	v_and_b32_e32 v5, 0xffff0000, v57
	v_pk_mul_f32 v[4:5], v[0:1], v[4:5] op_sel_hi:[0,1]
	v_cvt_pk_bf16_f32 v57, v4, v5
	global_store_dwordx4 v[6:7], v[54:57], off offset:1888
	s_waitcnt vmcnt(15)
	v_lshlrev_b32_e32 v4, 16, v58
	v_and_b32_e32 v5, 0xffff0000, v58
	v_pk_mul_f32 v[4:5], v[0:1], v[4:5] op_sel_hi:[0,1]
	v_cvt_pk_bf16_f32 v58, v4, v5
	v_lshlrev_b32_e32 v4, 16, v59
	v_and_b32_e32 v5, 0xffff0000, v59
	v_pk_mul_f32 v[4:5], v[0:1], v[4:5] op_sel_hi:[0,1]
	v_cvt_pk_bf16_f32 v59, v4, v5
	v_lshlrev_b32_e32 v4, 16, v60
	v_and_b32_e32 v5, 0xffff0000, v60
	v_pk_mul_f32 v[4:5], v[0:1], v[4:5] op_sel_hi:[0,1]
	v_cvt_pk_bf16_f32 v60, v4, v5
	v_lshlrev_b32_e32 v4, 16, v61
	v_and_b32_e32 v5, 0xffff0000, v61
	v_pk_mul_f32 v[4:5], v[0:1], v[4:5] op_sel_hi:[0,1]
	v_cvt_pk_bf16_f32 v61, v4, v5
	global_store_dwordx4 v[6:7], v[58:61], off offset:1920
	s_waitcnt vmcnt(15)
	v_lshlrev_b32_e32 v4, 16, v62
	v_and_b32_e32 v5, 0xffff0000, v62
	v_pk_mul_f32 v[4:5], v[0:1], v[4:5] op_sel_hi:[0,1]
	v_cvt_pk_bf16_f32 v62, v4, v5
	v_lshlrev_b32_e32 v4, 16, v63
	v_and_b32_e32 v5, 0xffff0000, v63
	v_pk_mul_f32 v[4:5], v[0:1], v[4:5] op_sel_hi:[0,1]
	v_cvt_pk_bf16_f32 v63, v4, v5
	v_lshlrev_b32_e32 v4, 16, v64
	v_and_b32_e32 v5, 0xffff0000, v64
	v_pk_mul_f32 v[4:5], v[0:1], v[4:5] op_sel_hi:[0,1]
	v_cvt_pk_bf16_f32 v64, v4, v5
	v_lshlrev_b32_e32 v4, 16, v65
	v_and_b32_e32 v5, 0xffff0000, v65
	v_pk_mul_f32 v[4:5], v[0:1], v[4:5] op_sel_hi:[0,1]
	v_cvt_pk_bf16_f32 v65, v4, v5
	global_store_dwordx4 v[6:7], v[62:65], off offset:1952
	s_waitcnt vmcnt(15)
	v_lshlrev_b32_e32 v4, 16, v66
	v_and_b32_e32 v5, 0xffff0000, v66
	v_pk_mul_f32 v[4:5], v[0:1], v[4:5] op_sel_hi:[0,1]
	v_cvt_pk_bf16_f32 v66, v4, v5
	v_lshlrev_b32_e32 v4, 16, v67
	v_and_b32_e32 v5, 0xffff0000, v67
	v_pk_mul_f32 v[4:5], v[0:1], v[4:5] op_sel_hi:[0,1]
	v_cvt_pk_bf16_f32 v67, v4, v5
	v_lshlrev_b32_e32 v4, 16, v68
	v_and_b32_e32 v5, 0xffff0000, v68
	v_pk_mul_f32 v[4:5], v[0:1], v[4:5] op_sel_hi:[0,1]
	v_cvt_pk_bf16_f32 v68, v4, v5
	v_lshlrev_b32_e32 v4, 16, v69
	v_and_b32_e32 v5, 0xffff0000, v69
	v_pk_mul_f32 v[4:5], v[0:1], v[4:5] op_sel_hi:[0,1]
	v_cvt_pk_bf16_f32 v69, v4, v5
	global_store_dwordx4 v[6:7], v[66:69], off offset:1984
	s_waitcnt vmcnt(15)
	v_lshlrev_b32_e32 v4, 16, v70
	v_and_b32_e32 v5, 0xffff0000, v70
	v_pk_mul_f32 v[4:5], v[0:1], v[4:5] op_sel_hi:[0,1]
	v_cvt_pk_bf16_f32 v70, v4, v5
	v_lshlrev_b32_e32 v4, 16, v71
	v_and_b32_e32 v5, 0xffff0000, v71
	v_pk_mul_f32 v[4:5], v[0:1], v[4:5] op_sel_hi:[0,1]
	v_cvt_pk_bf16_f32 v71, v4, v5
	v_lshlrev_b32_e32 v4, 16, v72
	v_and_b32_e32 v5, 0xffff0000, v72
	v_pk_mul_f32 v[4:5], v[0:1], v[4:5] op_sel_hi:[0,1]
	v_cvt_pk_bf16_f32 v72, v4, v5
	v_lshlrev_b32_e32 v4, 16, v73
	v_and_b32_e32 v5, 0xffff0000, v73
	v_pk_mul_f32 v[4:5], v[0:1], v[4:5] op_sel_hi:[0,1]
	v_cvt_pk_bf16_f32 v73, v4, v5
	global_store_dwordx4 v[6:7], v[70:73], off offset:2016

; DI float bf_lo(unsigned u) { return __uint_as_float(u << 16); }
; DI float bf_hi(unsigned u) { return __uint_as_float(u & 0xffff0000u); }
; DI float frsq(float x) { return __builtin_amdgcn_rsqf(x); }
; DI float xhalf(float v) { return __shfl_xor(v, 32); }
; DI void phase_attn(const Params& p, int layer, char* smem) {
;     ...
;       ssq += xhalf(ssq);
;       const float rstd = frsq(ssq * (1.f / 256.f) + EPS);
; #pragma unroll
;       for (int j = 0; j < 32; ++j) {
;         uint2* a = (uint2*)(ocat + (size_t)qtok * 1024 + 8 * j + 4 * h);
;         uint2 u = *a;
;         u.x = pk_bf16(bf_lo(u.x) * rstd, bf_hi(u.x) * rstd);
;         u.y = pk_bf16(bf_lo(u.y) * rstd, bf_hi(u.y) * rstd);
;         *a = u;
;       }
.LBB0_345:
	ds_bpermute_b32 v0, v206, v147
	v_lshlrev_b64 v[4:5], 11, v[148:149]
	v_lshl_add_u64 v[4:5], s[66:67], 0, v[4:5]
	v_readlane_b32 s48, v254, 60
	s_mov_b32 s49, 0xffff
	s_waitcnt lgkmcnt(0)
	v_add_f32_e32 v0, v147, v0
	v_fmamk_f32 v0, v0, 0x3b800000, v229
	v_rsq_f32_e32 v2, v0
	v_lshlrev_b32_e32 v0, 3, v215
	v_lshl_add_u64 v[4:5], v[4:5], 0, v[0:1]
	v_lshl_add_u64 v[4:5], v[4:5], 0, v[0:1]
	global_load_dwordx4 v[10:13], v[4:5], off
	global_load_dwordx4 v[14:17], v[4:5], off offset:32
	global_load_dwordx4 v[18:21], v[4:5], off offset:64
	global_load_dwordx4 v[22:25], v[4:5], off offset:96
	global_load_dwordx4 v[26:29], v[4:5], off offset:128
	global_load_dwordx4 v[30:33], v[4:5], off offset:160
	global_load_dwordx4 v[34:37], v[4:5], off offset:192
	global_load_dwordx4 v[38:41], v[4:5], off offset:224
	global_load_dwordx4 v[42:45], v[4:5], off offset:256
	global_load_dwordx4 v[46:49], v[4:5], off offset:288
	global_load_dwordx4 v[50:53], v[4:5], off offset:320
	global_load_dwordx4 v[54:57], v[4:5], off offset:352
	global_load_dwordx4 v[58:61], v[4:5], off offset:384
	global_load_dwordx4 v[62:65], v[4:5], off offset:416
	global_load_dwordx4 v[66:69], v[4:5], off offset:448
	global_load_dwordx4 v[70:73], v[4:5], off offset:480
	s_mov_b32 s47, s51
	s_mov_b32 s44, s57
	s_mov_b32 s8, s59
	s_waitcnt vmcnt(15)
	v_lshlrev_b32_e32 v8, 16, v10
	v_and_b32_e32 v9, 0xffff0000, v10
	v_pk_mul_f32 v[8:9], v[2:3], v[8:9] op_sel_hi:[0,1]
	v_cvt_pk_bf16_f32 v10, v8, v9
	v_lshlrev_b32_e32 v8, 16, v11
	v_and_b32_e32 v9, 0xffff0000, v11
	v_pk_mul_f32 v[8:9], v[2:3], v[8:9] op_sel_hi:[0,1]
	v_cvt_pk_bf16_f32 v11, v8, v9
	v_lshlrev_b32_e32 v8, 16, v12
	v_and_b32_e32 v9, 0xffff0000, v12
	v_pk_mul_f32 v[8:9], v[2:3], v[8:9] op_sel_hi:[0,1]
	v_cvt_pk_bf16_f32 v12, v8, v9
	v_lshlrev_b32_e32 v8, 16, v13
	v_and_b32_e32 v9, 0xffff0000, v13
	v_pk_mul_f32 v[8:9], v[2:3], v[8:9] op_sel_hi:[0,1]
	v_cvt_pk_bf16_f32 v13, v8, v9
	global_store_dwordx4 v[4:5], v[10:13], off
	s_waitcnt vmcnt(15)
	v_lshlrev_b32_e32 v8, 16, v14
	v_and_b32_e32 v9, 0xffff0000, v14
	v_pk_mul_f32 v[8:9], v[2:3], v[8:9] op_sel_hi:[0,1]
	v_cvt_pk_bf16_f32 v14, v8, v9
	v_lshlrev_b32_e32 v8, 16, v15
	v_and_b32_e32 v9, 0xffff0000, v15
	v_pk_mul_f32 v[8:9], v[2:3], v[8:9] op_sel_hi:[0,1]
	v_cvt_pk_bf16_f32 v15, v8, v9
	v_lshlrev_b32_e32 v8, 16, v16
	v_and_b32_e32 v9, 0xffff0000, v16
	v_pk_mul_f32 v[8:9], v[2:3], v[8:9] op_sel_hi:[0,1]
	v_cvt_pk_bf16_f32 v16, v8, v9
	v_lshlrev_b32_e32 v8, 16, v17
	v_and_b32_e32 v9, 0xffff0000, v17
	v_pk_mul_f32 v[8:9], v[2:3], v[8:9] op_sel_hi:[0,1]
	v_cvt_pk_bf16_f32 v17, v8, v9
	global_store_dwordx4 v[4:5], v[14:17], off offset:32
	s_waitcnt vmcnt(15)
	v_lshlrev_b32_e32 v8, 16, v18
	v_and_b32_e32 v9, 0xffff0000, v18
	v_pk_mul_f32 v[8:9], v[2:3], v[8:9] op_sel_hi:[0,1]
	v_cvt_pk_bf16_f32 v18, v8, v9
	v_lshlrev_b32_e32 v8, 16, v19
	v_and_b32_e32 v9, 0xffff0000, v19
	v_pk_mul_f32 v[8:9], v[2:3], v[8:9] op_sel_hi:[0,1]
	v_cvt_pk_bf16_f32 v19, v8, v9
	v_lshlrev_b32_e32 v8, 16, v20
	v_and_b32_e32 v9, 0xffff0000, v20
	v_pk_mul_f32 v[8:9], v[2:3], v[8:9] op_sel_hi:[0,1]
	v_cvt_pk_bf16_f32 v20, v8, v9
	v_lshlrev_b32_e32 v8, 16, v21
	v_and_b32_e32 v9, 0xffff0000, v21
	v_pk_mul_f32 v[8:9], v[2:3], v[8:9] op_sel_hi:[0,1]
	v_cvt_pk_bf16_f32 v21, v8, v9
	global_store_dwordx4 v[4:5], v[18:21], off offset:64
	s_waitcnt vmcnt(15)
	v_lshlrev_b32_e32 v8, 16, v22
	v_and_b32_e32 v9, 0xffff0000, v22
	v_pk_mul_f32 v[8:9], v[2:3], v[8:9] op_sel_hi:[0,1]
	v_cvt_pk_bf16_f32 v22, v8, v9
	v_lshlrev_b32_e32 v8, 16, v23
	v_and_b32_e32 v9, 0xffff0000, v23
	v_pk_mul_f32 v[8:9], v[2:3], v[8:9] op_sel_hi:[0,1]
	v_cvt_pk_bf16_f32 v23, v8, v9
	v_lshlrev_b32_e32 v8, 16, v24
	v_and_b32_e32 v9, 0xffff0000, v24
	v_pk_mul_f32 v[8:9], v[2:3], v[8:9] op_sel_hi:[0,1]
	v_cvt_pk_bf16_f32 v24, v8, v9
	v_lshlrev_b32_e32 v8, 16, v25
	v_and_b32_e32 v9, 0xffff0000, v25
	v_pk_mul_f32 v[8:9], v[2:3], v[8:9] op_sel_hi:[0,1]
	v_cvt_pk_bf16_f32 v25, v8, v9
	global_store_dwordx4 v[4:5], v[22:25], off offset:96
	s_waitcnt vmcnt(15)
	v_lshlrev_b32_e32 v8, 16, v26
	v_and_b32_e32 v9, 0xffff0000, v26
	v_pk_mul_f32 v[8:9], v[2:3], v[8:9] op_sel_hi:[0,1]
	v_cvt_pk_bf16_f32 v26, v8, v9
	v_lshlrev_b32_e32 v8, 16, v27
	v_and_b32_e32 v9, 0xffff0000, v27
	v_pk_mul_f32 v[8:9], v[2:3], v[8:9] op_sel_hi:[0,1]
	v_cvt_pk_bf16_f32 v27, v8, v9
	v_lshlrev_b32_e32 v8, 16, v28
	v_and_b32_e32 v9, 0xffff0000, v28
	v_pk_mul_f32 v[8:9], v[2:3], v[8:9] op_sel_hi:[0,1]
	v_cvt_pk_bf16_f32 v28, v8, v9
	v_lshlrev_b32_e32 v8, 16, v29
	v_and_b32_e32 v9, 0xffff0000, v29
	v_pk_mul_f32 v[8:9], v[2:3], v[8:9] op_sel_hi:[0,1]
	v_cvt_pk_bf16_f32 v29, v8, v9
	global_store_dwordx4 v[4:5], v[26:29], off offset:128
	s_waitcnt vmcnt(15)
	v_lshlrev_b32_e32 v8, 16, v30
	v_and_b32_e32 v9, 0xffff0000, v30
	v_pk_mul_f32 v[8:9], v[2:3], v[8:9] op_sel_hi:[0,1]
	v_cvt_pk_bf16_f32 v30, v8, v9
	v_lshlrev_b32_e32 v8, 16, v31
	v_and_b32_e32 v9, 0xffff0000, v31
	v_pk_mul_f32 v[8:9], v[2:3], v[8:9] op_sel_hi:[0,1]
	v_cvt_pk_bf16_f32 v31, v8, v9
	v_lshlrev_b32_e32 v8, 16, v32
	v_and_b32_e32 v9, 0xffff0000, v32
	v_pk_mul_f32 v[8:9], v[2:3], v[8:9] op_sel_hi:[0,1]
	v_cvt_pk_bf16_f32 v32, v8, v9
	v_lshlrev_b32_e32 v8, 16, v33
	v_and_b32_e32 v9, 0xffff0000, v33
	v_pk_mul_f32 v[8:9], v[2:3], v[8:9] op_sel_hi:[0,1]
	v_cvt_pk_bf16_f32 v33, v8, v9
	global_store_dwordx4 v[4:5], v[30:33], off offset:160
	s_waitcnt vmcnt(15)
; DI float bf_lo(unsigned u) { return __uint_as_float(u << 16); }
; DI float bf_hi(unsigned u) { return __uint_as_float(u & 0xffff0000u); }
; DI void phase_attn(const Params& p, int layer, char* smem) {
;     ...
;       for (int j = 0; j < 32; ++j) {
;         uint2* a = (uint2*)(ocat + (size_t)qtok * 1024 + 8 * j + 4 * h);
;         uint2 u = *a;
;         u.x = pk_bf16(bf_lo(u.x) * rstd, bf_hi(u.x) * rstd);
;         u.y = pk_bf16(bf_lo(u.y) * rstd, bf_hi(u.y) * rstd);
;         *a = u;
;       }
	v_lshlrev_b32_e32 v8, 16, v34
	v_and_b32_e32 v9, 0xffff0000, v34
	v_pk_mul_f32 v[8:9], v[2:3], v[8:9] op_sel_hi:[0,1]
	v_cvt_pk_bf16_f32 v34, v8, v9
	v_lshlrev_b32_e32 v8, 16, v35
	v_and_b32_e32 v9, 0xffff0000, v35
	v_pk_mul_f32 v[8:9], v[2:3], v[8:9] op_sel_hi:[0,1]
	v_cvt_pk_bf16_f32 v35, v8, v9
	v_lshlrev_b32_e32 v8, 16, v36
	v_and_b32_e32 v9, 0xffff0000, v36
	v_pk_mul_f32 v[8:9], v[2:3], v[8:9] op_sel_hi:[0,1]
	v_cvt_pk_bf16_f32 v36, v8, v9
	v_lshlrev_b32_e32 v8, 16, v37
	v_and_b32_e32 v9, 0xffff0000, v37
	v_pk_mul_f32 v[8:9], v[2:3], v[8:9] op_sel_hi:[0,1]
	v_cvt_pk_bf16_f32 v37, v8, v9
	global_store_dwordx4 v[4:5], v[34:37], off offset:192
	s_waitcnt vmcnt(15)
	v_lshlrev_b32_e32 v8, 16, v38
	v_and_b32_e32 v9, 0xffff0000, v38
	v_pk_mul_f32 v[8:9], v[2:3], v[8:9] op_sel_hi:[0,1]
	v_cvt_pk_bf16_f32 v38, v8, v9
	v_lshlrev_b32_e32 v8, 16, v39
	v_and_b32_e32 v9, 0xffff0000, v39
	v_pk_mul_f32 v[8:9], v[2:3], v[8:9] op_sel_hi:[0,1]
	v_cvt_pk_bf16_f32 v39, v8, v9
	v_lshlrev_b32_e32 v8, 16, v40
	v_and_b32_e32 v9, 0xffff0000, v40
	v_pk_mul_f32 v[8:9], v[2:3], v[8:9] op_sel_hi:[0,1]
	v_cvt_pk_bf16_f32 v40, v8, v9
	v_lshlrev_b32_e32 v8, 16, v41
	v_and_b32_e32 v9, 0xffff0000, v41
	v_pk_mul_f32 v[8:9], v[2:3], v[8:9] op_sel_hi:[0,1]
	v_cvt_pk_bf16_f32 v41, v8, v9
	global_store_dwordx4 v[4:5], v[38:41], off offset:224
	s_waitcnt vmcnt(15)
	v_lshlrev_b32_e32 v8, 16, v42
	v_and_b32_e32 v9, 0xffff0000, v42
	v_pk_mul_f32 v[8:9], v[2:3], v[8:9] op_sel_hi:[0,1]
	v_cvt_pk_bf16_f32 v42, v8, v9
	v_lshlrev_b32_e32 v8, 16, v43
	v_and_b32_e32 v9, 0xffff0000, v43
	v_pk_mul_f32 v[8:9], v[2:3], v[8:9] op_sel_hi:[0,1]
	v_cvt_pk_bf16_f32 v43, v8, v9
	v_lshlrev_b32_e32 v8, 16, v44
	v_and_b32_e32 v9, 0xffff0000, v44
	v_pk_mul_f32 v[8:9], v[2:3], v[8:9] op_sel_hi:[0,1]
	v_cvt_pk_bf16_f32 v44, v8, v9
	v_lshlrev_b32_e32 v8, 16, v45
	v_and_b32_e32 v9, 0xffff0000, v45
	v_pk_mul_f32 v[8:9], v[2:3], v[8:9] op_sel_hi:[0,1]
	v_cvt_pk_bf16_f32 v45, v8, v9
	global_store_dwordx4 v[4:5], v[42:45], off offset:256
	s_waitcnt vmcnt(15)
	v_lshlrev_b32_e32 v8, 16, v46
	v_and_b32_e32 v9, 0xffff0000, v46
	v_pk_mul_f32 v[8:9], v[2:3], v[8:9] op_sel_hi:[0,1]
	v_cvt_pk_bf16_f32 v46, v8, v9
	v_lshlrev_b32_e32 v8, 16, v47
	v_and_b32_e32 v9, 0xffff0000, v47
	v_pk_mul_f32 v[8:9], v[2:3], v[8:9] op_sel_hi:[0,1]
	v_cvt_pk_bf16_f32 v47, v8, v9
	v_lshlrev_b32_e32 v8, 16, v48
	v_and_b32_e32 v9, 0xffff0000, v48
	v_pk_mul_f32 v[8:9], v[2:3], v[8:9] op_sel_hi:[0,1]
	v_cvt_pk_bf16_f32 v48, v8, v9
	v_lshlrev_b32_e32 v8, 16, v49
	v_and_b32_e32 v9, 0xffff0000, v49
	v_pk_mul_f32 v[8:9], v[2:3], v[8:9] op_sel_hi:[0,1]
	v_cvt_pk_bf16_f32 v49, v8, v9
	global_store_dwordx4 v[4:5], v[46:49], off offset:288
	s_waitcnt vmcnt(15)
	v_lshlrev_b32_e32 v8, 16, v50
	v_and_b32_e32 v9, 0xffff0000, v50
	v_pk_mul_f32 v[8:9], v[2:3], v[8:9] op_sel_hi:[0,1]
	v_cvt_pk_bf16_f32 v50, v8, v9
	v_lshlrev_b32_e32 v8, 16, v51
	v_and_b32_e32 v9, 0xffff0000, v51
	v_pk_mul_f32 v[8:9], v[2:3], v[8:9] op_sel_hi:[0,1]
	v_cvt_pk_bf16_f32 v51, v8, v9
	v_lshlrev_b32_e32 v8, 16, v52
	v_and_b32_e32 v9, 0xffff0000, v52
	v_pk_mul_f32 v[8:9], v[2:3], v[8:9] op_sel_hi:[0,1]
	v_cvt_pk_bf16_f32 v52, v8, v9
	v_lshlrev_b32_e32 v8, 16, v53
	v_and_b32_e32 v9, 0xffff0000, v53
	v_pk_mul_f32 v[8:9], v[2:3], v[8:9] op_sel_hi:[0,1]
	v_cvt_pk_bf16_f32 v53, v8, v9
	global_store_dwordx4 v[4:5], v[50:53], off offset:320
	s_waitcnt vmcnt(15)
	v_lshlrev_b32_e32 v8, 16, v54
	v_and_b32_e32 v9, 0xffff0000, v54
	v_pk_mul_f32 v[8:9], v[2:3], v[8:9] op_sel_hi:[0,1]
	v_cvt_pk_bf16_f32 v54, v8, v9
	v_lshlrev_b32_e32 v8, 16, v55
	v_and_b32_e32 v9, 0xffff0000, v55
	v_pk_mul_f32 v[8:9], v[2:3], v[8:9] op_sel_hi:[0,1]
	v_cvt_pk_bf16_f32 v55, v8, v9
	v_lshlrev_b32_e32 v8, 16, v56
	v_and_b32_e32 v9, 0xffff0000, v56
	v_pk_mul_f32 v[8:9], v[2:3], v[8:9] op_sel_hi:[0,1]
	v_cvt_pk_bf16_f32 v56, v8, v9
	v_lshlrev_b32_e32 v8, 16, v57
	v_and_b32_e32 v9, 0xffff0000, v57
	v_pk_mul_f32 v[8:9], v[2:3], v[8:9] op_sel_hi:[0,1]
	v_cvt_pk_bf16_f32 v57, v8, v9
	global_store_dwordx4 v[4:5], v[54:57], off offset:352
	s_waitcnt vmcnt(15)
	v_lshlrev_b32_e32 v8, 16, v58
	v_and_b32_e32 v9, 0xffff0000, v58
	v_pk_mul_f32 v[8:9], v[2:3], v[8:9] op_sel_hi:[0,1]
	v_cvt_pk_bf16_f32 v58, v8, v9
	v_lshlrev_b32_e32 v8, 16, v59
	v_and_b32_e32 v9, 0xffff0000, v59
	v_pk_mul_f32 v[8:9], v[2:3], v[8:9] op_sel_hi:[0,1]
	v_cvt_pk_bf16_f32 v59, v8, v9
	v_lshlrev_b32_e32 v8, 16, v60
	v_and_b32_e32 v9, 0xffff0000, v60
	v_pk_mul_f32 v[8:9], v[2:3], v[8:9] op_sel_hi:[0,1]
	v_cvt_pk_bf16_f32 v60, v8, v9
	v_lshlrev_b32_e32 v8, 16, v61
	v_and_b32_e32 v9, 0xffff0000, v61
	v_pk_mul_f32 v[8:9], v[2:3], v[8:9] op_sel_hi:[0,1]
	v_cvt_pk_bf16_f32 v61, v8, v9
	global_store_dwordx4 v[4:5], v[58:61], off offset:384
	s_waitcnt vmcnt(15)
	v_lshlrev_b32_e32 v8, 16, v62
	v_and_b32_e32 v9, 0xffff0000, v62
	v_pk_mul_f32 v[8:9], v[2:3], v[8:9] op_sel_hi:[0,1]
	v_cvt_pk_bf16_f32 v62, v8, v9
	v_lshlrev_b32_e32 v8, 16, v63
	v_and_b32_e32 v9, 0xffff0000, v63
	v_pk_mul_f32 v[8:9], v[2:3], v[8:9] op_sel_hi:[0,1]
	v_cvt_pk_bf16_f32 v63, v8, v9
	v_lshlrev_b32_e32 v8, 16, v64
	v_and_b32_e32 v9, 0xffff0000, v64
	v_pk_mul_f32 v[8:9], v[2:3], v[8:9] op_sel_hi:[0,1]
	v_cvt_pk_bf16_f32 v64, v8, v9
	v_lshlrev_b32_e32 v8, 16, v65
	v_and_b32_e32 v9, 0xffff0000, v65
	v_pk_mul_f32 v[8:9], v[2:3], v[8:9] op_sel_hi:[0,1]
	v_cvt_pk_bf16_f32 v65, v8, v9
	global_store_dwordx4 v[4:5], v[62:65], off offset:416
	s_waitcnt vmcnt(15)
	v_lshlrev_b32_e32 v8, 16, v66
	v_and_b32_e32 v9, 0xffff0000, v66
	v_pk_mul_f32 v[8:9], v[2:3], v[8:9] op_sel_hi:[0,1]
	v_cvt_pk_bf16_f32 v66, v8, v9
	v_lshlrev_b32_e32 v8, 16, v67
	v_and_b32_e32 v9, 0xffff0000, v67
	v_pk_mul_f32 v[8:9], v[2:3], v[8:9] op_sel_hi:[0,1]
	v_cvt_pk_bf16_f32 v67, v8, v9
	v_lshlrev_b32_e32 v8, 16, v68
	v_and_b32_e32 v9, 0xffff0000, v68
	v_pk_mul_f32 v[8:9], v[2:3], v[8:9] op_sel_hi:[0,1]
	v_cvt_pk_bf16_f32 v68, v8, v9
	v_lshlrev_b32_e32 v8, 16, v69
	v_and_b32_e32 v9, 0xffff0000, v69
	v_pk_mul_f32 v[8:9], v[2:3], v[8:9] op_sel_hi:[0,1]
	v_cvt_pk_bf16_f32 v69, v8, v9
	global_store_dwordx4 v[4:5], v[66:69], off offset:448
	s_waitcnt vmcnt(15)
	v_lshlrev_b32_e32 v8, 16, v70
	v_and_b32_e32 v9, 0xffff0000, v70
	v_pk_mul_f32 v[8:9], v[2:3], v[8:9] op_sel_hi:[0,1]
	v_cvt_pk_bf16_f32 v70, v8, v9
	v_lshlrev_b32_e32 v8, 16, v71
	v_and_b32_e32 v9, 0xffff0000, v71
	v_pk_mul_f32 v[8:9], v[2:3], v[8:9] op_sel_hi:[0,1]
	v_cvt_pk_bf16_f32 v71, v8, v9
	v_lshlrev_b32_e32 v8, 16, v72
	v_and_b32_e32 v9, 0xffff0000, v72
	v_pk_mul_f32 v[8:9], v[2:3], v[8:9] op_sel_hi:[0,1]
	v_cvt_pk_bf16_f32 v72, v8, v9
	v_lshlrev_b32_e32 v8, 16, v73
	v_and_b32_e32 v9, 0xffff0000, v73
	v_pk_mul_f32 v[8:9], v[2:3], v[8:9] op_sel_hi:[0,1]
	v_cvt_pk_bf16_f32 v73, v8, v9
	global_store_dwordx4 v[4:5], v[70:73], off offset:480

; DI float bf_lo(unsigned u) { return __uint_as_float(u << 16); }
; DI float bf_hi(unsigned u) { return __uint_as_float(u & 0xffff0000u); }
; DI void phase_attn(const Params& p, int layer, char* smem) {
;     ...
; #pragma unroll 4
;       for (int j = 0; j < 64; ++j) {
;         const int tk = (j < 32) ? tA3 : tA3 + 32;
;         const float rs = (j < 32) ? rstdA : rstdB;
;         uint2* a = (uint2*)(ocat + (size_t)tk * 1024 + 256 + 8 * (j & 31) + 4 * h3);
;         uint2 u = *a;
;         u.x = pk_bf16(bf_lo(u.x) * rs, bf_hi(u.x) * rs);
;         u.y = pk_bf16(bf_lo(u.y) * rs, bf_hi(u.y) * rs);
;         *a = u;
;       }
.LBB0_382:
	v_and_or_b32 v6, s1, 32, v4
	s_cmp_lt_u32 s1, 32
	v_ashrrev_i32_e32 v7, 31, v6
	s_cselect_b64 vcc, -1, 0
	v_lshlrev_b64 v[6:7], 11, v[6:7]
	s_and_b32 s2, s1, 24
	v_lshl_add_u64 v[6:7], s[66:67], 0, v[6:7]
	s_lshl_b32 s34, s2, 4
	v_lshl_add_u64 v[6:7], v[6:7], 0, s[34:35]
	v_lshl_add_u64 v[6:7], v[6:7], 0, v[0:1]
	v_lshl_add_u64 v[6:7], v[6:7], 0, v[0:1]
	global_load_dwordx4 v[14:17], v[6:7], off offset:512
	global_load_dwordx4 v[18:21], v[6:7], off offset:544
	global_load_dwordx4 v[22:25], v[6:7], off offset:576
	global_load_dwordx4 v[26:29], v[6:7], off offset:608
	v_cndmask_b32_e32 v8, v3, v2, vcc
	s_add_i32 s1, s1, 8
	s_cmp_eq_u32 s1, 64
	s_waitcnt vmcnt(3)
	v_lshlrev_b32_e32 v12, 16, v14
	v_and_b32_e32 v13, 0xffff0000, v14
	v_pk_mul_f32 v[12:13], v[8:9], v[12:13] op_sel_hi:[0,1]
	v_cvt_pk_bf16_f32 v14, v12, v13
	v_lshlrev_b32_e32 v12, 16, v15
	v_and_b32_e32 v13, 0xffff0000, v15
	v_pk_mul_f32 v[12:13], v[8:9], v[12:13] op_sel_hi:[0,1]
	v_cvt_pk_bf16_f32 v15, v12, v13
	v_lshlrev_b32_e32 v12, 16, v16
	v_and_b32_e32 v13, 0xffff0000, v16
	v_pk_mul_f32 v[12:13], v[8:9], v[12:13] op_sel_hi:[0,1]
	v_cvt_pk_bf16_f32 v16, v12, v13
	v_lshlrev_b32_e32 v12, 16, v17
	v_and_b32_e32 v13, 0xffff0000, v17
	v_pk_mul_f32 v[12:13], v[8:9], v[12:13] op_sel_hi:[0,1]
	v_cvt_pk_bf16_f32 v17, v12, v13
	global_store_dwordx4 v[6:7], v[14:17], off offset:512
	s_waitcnt vmcnt(3)
	v_lshlrev_b32_e32 v12, 16, v18
	v_and_b32_e32 v13, 0xffff0000, v18
	v_pk_mul_f32 v[12:13], v[8:9], v[12:13] op_sel_hi:[0,1]
	v_cvt_pk_bf16_f32 v18, v12, v13
	v_lshlrev_b32_e32 v12, 16, v19
	v_and_b32_e32 v13, 0xffff0000, v19
	v_pk_mul_f32 v[12:13], v[8:9], v[12:13] op_sel_hi:[0,1]
	v_cvt_pk_bf16_f32 v19, v12, v13
	v_lshlrev_b32_e32 v12, 16, v20
	v_and_b32_e32 v13, 0xffff0000, v20
	v_pk_mul_f32 v[12:13], v[8:9], v[12:13] op_sel_hi:[0,1]
	v_cvt_pk_bf16_f32 v20, v12, v13
	v_lshlrev_b32_e32 v12, 16, v21
	v_and_b32_e32 v13, 0xffff0000, v21
	v_pk_mul_f32 v[12:13], v[8:9], v[12:13] op_sel_hi:[0,1]
	v_cvt_pk_bf16_f32 v21, v12, v13
	global_store_dwordx4 v[6:7], v[18:21], off offset:544
	s_waitcnt vmcnt(3)
	v_lshlrev_b32_e32 v12, 16, v22
	v_and_b32_e32 v13, 0xffff0000, v22
	v_pk_mul_f32 v[12:13], v[8:9], v[12:13] op_sel_hi:[0,1]
	v_cvt_pk_bf16_f32 v22, v12, v13
	v_lshlrev_b32_e32 v12, 16, v23
	v_and_b32_e32 v13, 0xffff0000, v23
	v_pk_mul_f32 v[12:13], v[8:9], v[12:13] op_sel_hi:[0,1]
	v_cvt_pk_bf16_f32 v23, v12, v13
	v_lshlrev_b32_e32 v12, 16, v24
	v_and_b32_e32 v13, 0xffff0000, v24
	v_pk_mul_f32 v[12:13], v[8:9], v[12:13] op_sel_hi:[0,1]
	v_cvt_pk_bf16_f32 v24, v12, v13
	v_lshlrev_b32_e32 v12, 16, v25
	v_and_b32_e32 v13, 0xffff0000, v25
	v_pk_mul_f32 v[12:13], v[8:9], v[12:13] op_sel_hi:[0,1]
	v_cvt_pk_bf16_f32 v25, v12, v13
	global_store_dwordx4 v[6:7], v[22:25], off offset:576
	s_waitcnt vmcnt(3)
	v_lshlrev_b32_e32 v12, 16, v26
	v_and_b32_e32 v13, 0xffff0000, v26
	v_pk_mul_f32 v[12:13], v[8:9], v[12:13] op_sel_hi:[0,1]
	v_cvt_pk_bf16_f32 v26, v12, v13
	v_lshlrev_b32_e32 v12, 16, v27
	v_and_b32_e32 v13, 0xffff0000, v27
	v_pk_mul_f32 v[12:13], v[8:9], v[12:13] op_sel_hi:[0,1]
	v_cvt_pk_bf16_f32 v27, v12, v13
	v_lshlrev_b32_e32 v12, 16, v28
	v_and_b32_e32 v13, 0xffff0000, v28
	v_pk_mul_f32 v[12:13], v[8:9], v[12:13] op_sel_hi:[0,1]
	v_cvt_pk_bf16_f32 v28, v12, v13
	v_lshlrev_b32_e32 v12, 16, v29
	v_and_b32_e32 v13, 0xffff0000, v29
	v_pk_mul_f32 v[12:13], v[8:9], v[12:13] op_sel_hi:[0,1]
	v_cvt_pk_bf16_f32 v29, v12, v13
	global_store_dwordx4 v[6:7], v[26:29], off offset:608
	s_cbranch_scc0 .LBB0_382
